# P7 out-proj epilogue: 32 serialized X loads (each vmcnt(0)) replaced by rolling prefetch 3 row-groups ahead, acc+=X first, then stores/atomics
# speedup vs baseline: 1.0137x; 1.0010x over previous
; #define G_STAGE(bufoff, gbase, voff) do { _Pragma("unroll") for (int _i = 0; _i < 2; ++_i) \
;         __builtin_amdgcn_global_load_lds((const unsigned*)((const char*)(gbase) + (voff)[_i]), (LAS unsigned*)(lds + (bufoff) + ldsw + _i * 8192), 16, 0, 0); } while (0)
; #define G_LDA(dst, b, h) do { _Pragma("unroll") for (int m = 0; m < 4; ++m) _Pragma("unroll") for (int k = 0; k < 2; ++k) dst[m][k] = *(const LAS bf16x8*)(lds + G_SA(b, h) + aoff + m * 2048 + k * 1024); } while (0)
; #define G_LDB(dst, b, h) do { _Pragma("unroll") for (int n = 0; n < 2; ++n) _Pragma("unroll") for (int k = 0; k < 2; ++k) dst[n][k] = *(const LAS bf16x8*)(lds + G_SB(b, h) + boff + n * 2048 + k * 1024); } while (0)
; #define G_MMA(ai, bj, At, Bt) do { __builtin_amdgcn_s_setprio(1); _Pragma("unroll") for (int m = 0; m < 4; ++m) _Pragma("unroll") for (int n = 0; n < 2; ++n) _Pragma("unroll") for (int k = 0; k < 2; ++k) \
;         acc[ai][bj][m][n] = __builtin_amdgcn_mfma_f32_16x16x32_bf16(Bt[n][k], At[m][k], acc[ai][bj][m][n], 0, 0, 0); __builtin_amdgcn_s_setprio(0); } while (0)
; #define G_WAIT_V(n) asm volatile("s_waitcnt vmcnt(" #n ")" ::: "memory")
; #define G_WAIT_L(n) asm volatile("s_waitcnt lgkmcnt(" #n ")" ::: "memory")
; #define G_BAR __builtin_amdgcn_s_barrier()
; #define G_SCHED __builtin_amdgcn_sched_barrier(0)
; template <bool PERM, class Dec, class Epi>
; DI void gemm_phase(LAS unsigned char* lds, const int nM, const int nN, const int K, const int lda, const int ldb, const Dec& dec, const Epi& epi, const int vb, const int panel = -1) {
;     ...
;             G_LDB(B0, 0, 0); G_SCHED; G_LDA(At, 0, 0); G_STAGE(G_SA(1, 1), a1 + hstepA, voffA);
;             G_WAIT_L(8); G_BAR; G_WAIT_L(0); G_MMA(0, 0, At, B0); G_BAR; G_SCHED;
;             G_LDB(B1, 0, 1); G_STAGE(G_SB(0, 0), b2, voffB);
;             G_BAR; G_WAIT_L(0); G_MMA(0, 1, At, B1); G_BAR;
;             G_LDA(At, 0, 1); G_STAGE(G_SA(0, 0), a2, voffA);
;             G_BAR; G_WAIT_L(0); G_MMA(1, 0, At, B0); G_BAR; G_SCHED;
;             G_STAGE(G_SB(0, 1), b2 + hstepB, voffB);
;             G_WAIT_V(6); G_BAR; G_MMA(1, 1, At, B1); G_BAR;
;             G_LDB(B0, 1, 0); G_SCHED; G_LDA(At, 1, 0); G_STAGE(G_SA(0, 1), a2 + hstepA, voffA);
;             G_WAIT_L(8); G_BAR; G_WAIT_L(0); G_MMA(0, 0, At, B0); G_BAR; G_SCHED;
.LBB0_670:
	s_add_u32 s50, s2, 0xfff80080
	s_addc_u32 s51, s3, -1
	s_add_i32 s64, 0, 0x10000
	v_add_u32_e32 v149, s64, v147
	ds_read_b128 v[142:145], v149
	ds_read_b128 v[150:153], v149 offset:1024
	ds_read_b128 v[154:157], v149 offset:2048
	ds_read_b128 v[158:161], v149 offset:3072
	s_cmp_eq_u32 s75, 28
	s_cselect_b32 s53, s35, s51
	s_cselect_b32 s52, s37, s50
	s_cselect_b32 s51, s71, s74
	s_cselect_b32 s50, s72, s73
	v_lshl_add_u64 v[198:199], s[2:3], 0, v[138:139]
	s_add_i32 m0, s54, 0xc000
	ds_read_b128 v[162:165], v148
	ds_read_b128 v[166:169], v148 offset:1024
	ds_read_b128 v[170:173], v148 offset:2048
	ds_read_b128 v[176:179], v148 offset:3072
	ds_read_b128 v[180:183], v148 offset:4096
	ds_read_b128 v[184:187], v148 offset:5120
	ds_read_b128 v[188:191], v148 offset:6144
	ds_read_b128 v[194:197], v148 offset:7168
	global_load_lds_dwordx4 v[198:199], off
	v_lshl_add_u64 v[198:199], s[2:3], 0, v[140:141]
	s_add_i32 m0, s54, 0xe000
	s_nop 0
	global_load_lds_dwordx4 v[198:199], off
	s_waitcnt lgkmcnt(8)
	s_barrier
	s_waitcnt lgkmcnt(0)
	s_setprio 1
	s_waitcnt lgkmcnt(0)
	v_mfma_f32_16x16x32_bf16 v[124:127], v[142:145], v[162:165], v[124:127]
	v_mfma_f32_16x16x32_bf16 v[120:123], v[154:157], v[162:165], v[120:123]
	v_mfma_f32_16x16x32_bf16 v[108:111], v[142:145], v[170:173], v[108:111]
	v_mfma_f32_16x16x32_bf16 v[104:107], v[154:157], v[170:173], v[104:107]
	v_mfma_f32_16x16x32_bf16 v[92:95], v[142:145], v[180:183], v[92:95]
	v_mfma_f32_16x16x32_bf16 v[88:91], v[154:157], v[180:183], v[88:91]
	v_mfma_f32_16x16x32_bf16 v[76:79], v[142:145], v[188:191], v[76:79]
	v_mfma_f32_16x16x32_bf16 v[72:75], v[154:157], v[188:191], v[72:75]
	v_mfma_f32_16x16x32_bf16 v[124:127], v[150:153], v[166:169], v[124:127]
	v_mfma_f32_16x16x32_bf16 v[120:123], v[158:161], v[166:169], v[120:123]
	v_mfma_f32_16x16x32_bf16 v[108:111], v[150:153], v[176:179], v[108:111]
	v_mfma_f32_16x16x32_bf16 v[104:107], v[158:161], v[176:179], v[104:107]
	v_mfma_f32_16x16x32_bf16 v[92:95], v[150:153], v[184:187], v[92:95]
	v_mfma_f32_16x16x32_bf16 v[88:91], v[158:161], v[184:187], v[88:91]
	v_mfma_f32_16x16x32_bf16 v[76:79], v[150:153], v[194:197], v[76:79]
	v_mfma_f32_16x16x32_bf16 v[72:75], v[158:161], v[194:197], v[72:75]
	s_setprio 0
	s_barrier
	s_add_i32 s68, 0, 0x14000
	s_add_i32 s64, s64, s39
	v_add_u32_e32 v149, s68, v147
	v_lshl_add_u64 v[214:215], s[50:51], 0, v[128:129]
	s_mov_b32 m0, s64
	ds_read_b128 v[198:201], v149
	ds_read_b128 v[202:205], v149 offset:1024
	ds_read_b128 v[206:209], v149 offset:2048
	ds_read_b128 v[210:213], v149 offset:3072
	global_load_lds_dwordx4 v[214:215], off
	v_lshl_add_u64 v[216:217], s[50:51], 0, v[134:135]
	s_add_i32 m0, s64, 0x2000
	s_nop 0
	global_load_lds_dwordx4 v[216:217], off
	s_barrier
	s_waitcnt lgkmcnt(0)
	s_setprio 1
	s_waitcnt lgkmcnt(0)
	v_mfma_f32_16x16x32_bf16 v[116:119], v[198:201], v[162:165], v[116:119]
	v_mfma_f32_16x16x32_bf16 v[112:115], v[206:209], v[162:165], v[112:115]
	v_mfma_f32_16x16x32_bf16 v[100:103], v[198:201], v[170:173], v[100:103]
	v_mfma_f32_16x16x32_bf16 v[96:99], v[206:209], v[170:173], v[96:99]
	v_mfma_f32_16x16x32_bf16 v[84:87], v[198:201], v[180:183], v[84:87]
	v_mfma_f32_16x16x32_bf16 v[80:83], v[206:209], v[180:183], v[80:83]
	v_mfma_f32_16x16x32_bf16 v[68:71], v[198:201], v[188:191], v[68:71]
	v_mfma_f32_16x16x32_bf16 v[64:67], v[206:209], v[188:191], v[64:67]
	v_mfma_f32_16x16x32_bf16 v[116:119], v[202:205], v[166:169], v[116:119]
	v_mfma_f32_16x16x32_bf16 v[112:115], v[210:213], v[166:169], v[112:115]
	v_mfma_f32_16x16x32_bf16 v[100:103], v[202:205], v[176:179], v[100:103]
	v_mfma_f32_16x16x32_bf16 v[96:99], v[210:213], v[176:179], v[96:99]
	v_mfma_f32_16x16x32_bf16 v[84:87], v[202:205], v[184:187], v[84:87]
	v_mfma_f32_16x16x32_bf16 v[80:83], v[210:213], v[184:187], v[80:83]
	v_mfma_f32_16x16x32_bf16 v[68:71], v[202:205], v[194:197], v[68:71]
	v_mfma_f32_16x16x32_bf16 v[64:67], v[210:213], v[194:197], v[64:67]
	s_setprio 0
	s_mov_b32 m0, s54
	v_lshl_add_u64 v[218:219], s[52:53], 0, v[128:129]
	s_barrier
	ds_read_b128 v[162:165], v148 offset:16384
	ds_read_b128 v[166:169], v148 offset:17408
	ds_read_b128 v[170:173], v148 offset:18432
	ds_read_b128 v[176:179], v148 offset:19456
	ds_read_b128 v[180:183], v148 offset:20480
	ds_read_b128 v[184:187], v148 offset:21504
	ds_read_b128 v[188:191], v148 offset:22528
	ds_read_b128 v[194:197], v148 offset:23552
	global_load_lds_dwordx4 v[218:219], off
	v_lshl_add_u64 v[220:221], s[52:53], 0, v[134:135]
	s_mov_b32 m0, s55
	s_nop 0
	global_load_lds_dwordx4 v[220:221], off
	s_barrier
	s_waitcnt lgkmcnt(0)
	s_setprio 1
	s_waitcnt lgkmcnt(0)
	v_mfma_f32_16x16x32_bf16 v[60:63], v[142:145], v[162:165], v[60:63]
	v_mfma_f32_16x16x32_bf16 v[56:59], v[154:157], v[162:165], v[56:59]
	v_mfma_f32_16x16x32_bf16 v[44:47], v[142:145], v[170:173], v[44:47]
	v_mfma_f32_16x16x32_bf16 v[40:43], v[154:157], v[170:173], v[40:43]
	v_mfma_f32_16x16x32_bf16 v[28:31], v[142:145], v[180:183], v[28:31]
	v_mfma_f32_16x16x32_bf16 v[24:27], v[154:157], v[180:183], v[24:27]
	v_mfma_f32_16x16x32_bf16 v[12:15], v[142:145], v[188:191], v[12:15]
	v_mfma_f32_16x16x32_bf16 v[8:11], v[154:157], v[188:191], v[8:11]
	v_mfma_f32_16x16x32_bf16 v[60:63], v[150:153], v[166:169], v[60:63]
	v_mfma_f32_16x16x32_bf16 v[56:59], v[158:161], v[166:169], v[56:59]
	v_mfma_f32_16x16x32_bf16 v[44:47], v[150:153], v[176:179], v[44:47]
	v_mfma_f32_16x16x32_bf16 v[40:43], v[158:161], v[176:179], v[40:43]
	v_mfma_f32_16x16x32_bf16 v[28:31], v[150:153], v[184:187], v[28:31]
	v_mfma_f32_16x16x32_bf16 v[24:27], v[158:161], v[184:187], v[24:27]
	v_mfma_f32_16x16x32_bf16 v[12:15], v[150:153], v[194:197], v[12:15]
	v_mfma_f32_16x16x32_bf16 v[8:11], v[158:161], v[194:197], v[8:11]
	s_setprio 0
	s_barrier
; #define G_STAGE(bufoff, gbase, voff) do { _Pragma("unroll") for (int _i = 0; _i < 2; ++_i) \
;         __builtin_amdgcn_global_load_lds((const unsigned*)((const char*)(gbase) + (voff)[_i]), (LAS unsigned*)(lds + (bufoff) + ldsw + _i * 8192), 16, 0, 0); } while (0)
; #define G_LDA(dst, b, h) do { _Pragma("unroll") for (int m = 0; m < 4; ++m) _Pragma("unroll") for (int k = 0; k < 2; ++k) dst[m][k] = *(const LAS bf16x8*)(lds + G_SA(b, h) + aoff + m * 2048 + k * 1024); } while (0)
; #define G_LDB(dst, b, h) do { _Pragma("unroll") for (int n = 0; n < 2; ++n) _Pragma("unroll") for (int k = 0; k < 2; ++k) dst[n][k] = *(const LAS bf16x8*)(lds + G_SB(b, h) + boff + n * 2048 + k * 1024); } while (0)
; #define G_MMA(ai, bj, At, Bt) do { __builtin_amdgcn_s_setprio(1); _Pragma("unroll") for (int m = 0; m < 4; ++m) _Pragma("unroll") for (int n = 0; n < 2; ++n) _Pragma("unroll") for (int k = 0; k < 2; ++k) \
;         acc[ai][bj][m][n] = __builtin_amdgcn_mfma_f32_16x16x32_bf16(Bt[n][k], At[m][k], acc[ai][bj][m][n], 0, 0, 0); __builtin_amdgcn_s_setprio(0); } while (0)
; #define G_WAIT_V(n) asm volatile("s_waitcnt vmcnt(" #n ")" ::: "memory")
; #define G_WAIT_L(n) asm volatile("s_waitcnt lgkmcnt(" #n ")" ::: "memory")
; #define G_BAR __builtin_amdgcn_s_barrier()
; #define G_SCHED __builtin_amdgcn_sched_barrier(0)
; template <bool PERM, class Dec, class Epi>
; DI void gemm_phase(LAS unsigned char* lds, const int nM, const int nN, const int K, const int lda, const int ldb, const Dec& dec, const Epi& epi, const int vb, const int panel = -1) {
;     ...
;             G_STAGE(G_SB(0, 1), b2 + hstepB, voffB);
;             G_WAIT_V(6); G_BAR; G_MMA(1, 1, At, B1); G_BAR;
;             G_LDB(B0, 1, 0); G_SCHED; G_LDA(At, 1, 0); G_STAGE(G_SA(0, 1), a2 + hstepA, voffA);
;             G_WAIT_L(8); G_BAR; G_WAIT_L(0); G_MMA(0, 0, At, B0); G_BAR; G_SCHED;
;             G_LDB(B1, 1, 1); G_STAGE(G_SB(1, 0), b3, voffB);
;             G_BAR; G_WAIT_L(0); G_MMA(0, 1, At, B1); G_BAR;
;             G_LDA(At, 1, 1); G_STAGE(G_SA(1, 0), a3, voffA);
;             G_BAR; G_WAIT_L(0); G_MMA(1, 0, At, B0); G_BAR; G_SCHED;
;             G_STAGE(G_SB(1, 1), b3 + hstepB, voffB);
	s_add_u32 s64, s50, 0x80000
	s_addc_u32 s65, s51, 0
	s_add_i32 s68, s68, s39
	v_lshl_add_u64 v[142:143], s[64:65], 0, v[128:129]
	s_mov_b32 m0, s68
	s_nop 0
	global_load_lds_dwordx4 v[142:143], off
	v_lshl_add_u64 v[142:143], s[64:65], 0, v[134:135]
	s_add_i32 m0, s68, 0x2000
	s_nop 0
	global_load_lds_dwordx4 v[142:143], off
	s_waitcnt vmcnt(6)
	s_barrier
	s_setprio 1
	v_mfma_f32_16x16x32_bf16 v[52:55], v[198:201], v[162:165], v[52:55]
	v_mfma_f32_16x16x32_bf16 v[48:51], v[206:209], v[162:165], v[48:51]
	v_mfma_f32_16x16x32_bf16 v[36:39], v[198:201], v[170:173], v[36:39]
	v_mfma_f32_16x16x32_bf16 v[32:35], v[206:209], v[170:173], v[32:35]
	v_mfma_f32_16x16x32_bf16 v[20:23], v[198:201], v[180:183], v[20:23]
	v_mfma_f32_16x16x32_bf16 v[16:19], v[206:209], v[180:183], v[16:19]
	v_mfma_f32_16x16x32_bf16 v[4:7], v[198:201], v[188:191], v[4:7]
	v_mfma_f32_16x16x32_bf16 v[0:3], v[206:209], v[188:191], v[0:3]
	v_mfma_f32_16x16x32_bf16 v[52:55], v[202:205], v[166:169], v[52:55]
	v_mfma_f32_16x16x32_bf16 v[48:51], v[210:213], v[166:169], v[48:51]
	v_mfma_f32_16x16x32_bf16 v[36:39], v[202:205], v[176:179], v[36:39]
	v_mfma_f32_16x16x32_bf16 v[32:35], v[210:213], v[176:179], v[32:35]
	v_mfma_f32_16x16x32_bf16 v[20:23], v[202:205], v[184:187], v[20:23]
	v_mfma_f32_16x16x32_bf16 v[16:19], v[210:213], v[184:187], v[16:19]
	v_mfma_f32_16x16x32_bf16 v[4:7], v[202:205], v[194:197], v[4:7]
	v_mfma_f32_16x16x32_bf16 v[0:3], v[210:213], v[194:197], v[0:3]
	s_setprio 0
	s_add_i32 s64, 0, 0x18000
	v_add_u32_e32 v149, s64, v147
	s_barrier
	ds_read_b128 v[142:145], v149
	ds_read_b128 v[150:153], v149 offset:1024
	ds_read_b128 v[154:157], v149 offset:2048
	ds_read_b128 v[158:161], v149 offset:3072
	s_add_u32 s52, s52, 0x80000
	s_addc_u32 s53, s53, 0
	s_mov_b32 m0, s58
	v_lshl_add_u64 v[198:199], s[52:53], 0, v[128:129]
	ds_read_b128 v[162:165], v148 offset:32768
	ds_read_b128 v[166:169], v148 offset:33792
	ds_read_b128 v[170:173], v148 offset:34816
	ds_read_b128 v[176:179], v148 offset:35840
	ds_read_b128 v[180:183], v148 offset:36864
	ds_read_b128 v[184:187], v148 offset:37888
	ds_read_b128 v[188:191], v148 offset:38912
	ds_read_b128 v[194:197], v148 offset:39936
	global_load_lds_dwordx4 v[198:199], off
	v_lshl_add_u64 v[198:199], s[52:53], 0, v[134:135]
	s_mov_b32 m0, s59
	s_nop 0
	global_load_lds_dwordx4 v[198:199], off
	s_waitcnt lgkmcnt(8)
	s_barrier
	s_waitcnt lgkmcnt(0)
	s_setprio 1
	s_waitcnt lgkmcnt(0)
	v_mfma_f32_16x16x32_bf16 v[124:127], v[142:145], v[162:165], v[124:127]
	v_mfma_f32_16x16x32_bf16 v[120:123], v[154:157], v[162:165], v[120:123]
	v_mfma_f32_16x16x32_bf16 v[108:111], v[142:145], v[170:173], v[108:111]
	v_mfma_f32_16x16x32_bf16 v[104:107], v[154:157], v[170:173], v[104:107]
	v_mfma_f32_16x16x32_bf16 v[92:95], v[142:145], v[180:183], v[92:95]
	v_mfma_f32_16x16x32_bf16 v[88:91], v[154:157], v[180:183], v[88:91]
	v_mfma_f32_16x16x32_bf16 v[76:79], v[142:145], v[188:191], v[76:79]
	v_mfma_f32_16x16x32_bf16 v[72:75], v[154:157], v[188:191], v[72:75]
	v_mfma_f32_16x16x32_bf16 v[124:127], v[150:153], v[166:169], v[124:127]
	v_mfma_f32_16x16x32_bf16 v[120:123], v[158:161], v[166:169], v[120:123]
	v_mfma_f32_16x16x32_bf16 v[108:111], v[150:153], v[176:179], v[108:111]
	v_mfma_f32_16x16x32_bf16 v[104:107], v[158:161], v[176:179], v[104:107]
	v_mfma_f32_16x16x32_bf16 v[92:95], v[150:153], v[184:187], v[92:95]
	v_mfma_f32_16x16x32_bf16 v[88:91], v[158:161], v[184:187], v[88:91]
	v_mfma_f32_16x16x32_bf16 v[76:79], v[150:153], v[194:197], v[76:79]
	v_mfma_f32_16x16x32_bf16 v[72:75], v[158:161], v[194:197], v[72:75]
	s_setprio 0
	s_barrier
	s_add_i32 s52, 0, 0x1c000
	s_add_i32 s53, s64, s39
	v_add_u32_e32 v149, s52, v147
	v_lshl_add_u64 v[214:215], v[214:215], 0, s[30:31]
	s_mov_b32 m0, s53
	ds_read_b128 v[198:201], v149
	ds_read_b128 v[202:205], v149 offset:1024
	ds_read_b128 v[206:209], v149 offset:2048
	ds_read_b128 v[210:213], v149 offset:3072
	global_load_lds_dwordx4 v[214:215], off
	v_lshl_add_u64 v[214:215], v[216:217], 0, s[30:31]
	s_add_i32 m0, s53, 0x2000
	s_nop 0
	global_load_lds_dwordx4 v[214:215], off
	s_barrier
	s_waitcnt lgkmcnt(0)
	s_setprio 1
	s_waitcnt lgkmcnt(0)
	v_mfma_f32_16x16x32_bf16 v[116:119], v[198:201], v[162:165], v[116:119]
	v_mfma_f32_16x16x32_bf16 v[112:115], v[206:209], v[162:165], v[112:115]
	v_mfma_f32_16x16x32_bf16 v[100:103], v[198:201], v[170:173], v[100:103]
	v_mfma_f32_16x16x32_bf16 v[96:99], v[206:209], v[170:173], v[96:99]
	v_mfma_f32_16x16x32_bf16 v[84:87], v[198:201], v[180:183], v[84:87]
	v_mfma_f32_16x16x32_bf16 v[80:83], v[206:209], v[180:183], v[80:83]
	v_mfma_f32_16x16x32_bf16 v[68:71], v[198:201], v[188:191], v[68:71]
	v_mfma_f32_16x16x32_bf16 v[64:67], v[206:209], v[188:191], v[64:67]
	v_mfma_f32_16x16x32_bf16 v[116:119], v[202:205], v[166:169], v[116:119]
	v_mfma_f32_16x16x32_bf16 v[112:115], v[210:213], v[166:169], v[112:115]
	v_mfma_f32_16x16x32_bf16 v[100:103], v[202:205], v[176:179], v[100:103]
	v_mfma_f32_16x16x32_bf16 v[96:99], v[210:213], v[176:179], v[96:99]
	v_mfma_f32_16x16x32_bf16 v[84:87], v[202:205], v[184:187], v[84:87]
	v_mfma_f32_16x16x32_bf16 v[80:83], v[210:213], v[184:187], v[80:83]
	v_mfma_f32_16x16x32_bf16 v[68:71], v[202:205], v[194:197], v[68:71]
	v_mfma_f32_16x16x32_bf16 v[64:67], v[210:213], v[194:197], v[64:67]
	s_setprio 0
	s_mov_b32 m0, s62
	v_lshl_add_u64 v[214:215], v[218:219], 0, s[30:31]
	s_barrier
	ds_read_b128 v[162:165], v148 offset:49152
	ds_read_b128 v[166:169], v148 offset:50176
	ds_read_b128 v[170:173], v148 offset:51200
	ds_read_b128 v[176:179], v148 offset:52224
	ds_read_b128 v[180:183], v148 offset:53248
	ds_read_b128 v[184:187], v148 offset:54272
	ds_read_b128 v[188:191], v148 offset:55296
	ds_read_b128 v[194:197], v148 offset:56320
	global_load_lds_dwordx4 v[214:215], off
	v_lshl_add_u64 v[214:215], v[220:221], 0, s[30:31]
	s_mov_b32 m0, s63
	s_nop 0
	global_load_lds_dwordx4 v[214:215], off
	s_barrier
; #define G_STAGE(bufoff, gbase, voff) do { _Pragma("unroll") for (int _i = 0; _i < 2; ++_i) \
;         __builtin_amdgcn_global_load_lds((const unsigned*)((const char*)(gbase) + (voff)[_i]), (LAS unsigned*)(lds + (bufoff) + ldsw + _i * 8192), 16, 0, 0); } while (0)
; #define G_MMA(ai, bj, At, Bt) do { __builtin_amdgcn_s_setprio(1); _Pragma("unroll") for (int m = 0; m < 4; ++m) _Pragma("unroll") for (int n = 0; n < 2; ++n) _Pragma("unroll") for (int k = 0; k < 2; ++k) \
;         acc[ai][bj][m][n] = __builtin_amdgcn_mfma_f32_16x16x32_bf16(Bt[n][k], At[m][k], acc[ai][bj][m][n], 0, 0, 0); __builtin_amdgcn_s_setprio(0); } while (0)
; #define G_WAIT_V(n) asm volatile("s_waitcnt vmcnt(" #n ")" ::: "memory")
; #define G_WAIT_L(n) asm volatile("s_waitcnt lgkmcnt(" #n ")" ::: "memory")
; #define G_BAR __builtin_amdgcn_s_barrier()
; #define G_SCHED __builtin_amdgcn_sched_barrier(0)
; template <bool PERM, class Dec, class Epi>
; DI void gemm_phase(LAS unsigned char* lds, const int nM, const int nN, const int K, const int lda, const int ldb, const Dec& dec, const Epi& epi, const int vb, const int panel = -1) {
;     ...
;             G_BAR; G_WAIT_L(0); G_MMA(1, 0, At, B0); G_BAR; G_SCHED;
;             G_STAGE(G_SB(1, 1), b3 + hstepB, voffB);
;             G_WAIT_V(6); G_BAR; G_MMA(1, 1, At, B1); G_BAR;
; __global__ void __launch_bounds__(512) hybrid_fwd(Params p) {
;     ...
;                   for (int m = 0; m < 4; ++m) { const int row = pm * 256 + ai * 128 + wr * 64 + m * 16 + fr; const size_t ro = (size_t)row * 1024 + pn * 256 + wc * 32 + 4 * fq;
;                       float ssq = 0.f;
; #pragma unroll
;                       for (int bj = 0; bj < 2; ++bj)
; #pragma unroll
;                           for (int n = 0; n < 2; ++n) { const size_t o = ro + bj * 128 + n * 16; const f32x4 v = *(const f32x4*)(X + o) + acc[ai][bj][m][n];
	s_waitcnt lgkmcnt(0)
	s_setprio 1
	s_waitcnt lgkmcnt(0)
	v_mfma_f32_16x16x32_bf16 v[60:63], v[142:145], v[162:165], v[60:63]
	v_mfma_f32_16x16x32_bf16 v[56:59], v[154:157], v[162:165], v[56:59]
	v_mfma_f32_16x16x32_bf16 v[44:47], v[142:145], v[170:173], v[44:47]
	v_mfma_f32_16x16x32_bf16 v[40:43], v[154:157], v[170:173], v[40:43]
	v_mfma_f32_16x16x32_bf16 v[28:31], v[142:145], v[180:183], v[28:31]
	v_mfma_f32_16x16x32_bf16 v[24:27], v[154:157], v[180:183], v[24:27]
	v_mfma_f32_16x16x32_bf16 v[12:15], v[142:145], v[188:191], v[12:15]
	v_mfma_f32_16x16x32_bf16 v[8:11], v[154:157], v[188:191], v[8:11]
	v_mfma_f32_16x16x32_bf16 v[60:63], v[150:153], v[166:169], v[60:63]
	v_mfma_f32_16x16x32_bf16 v[56:59], v[158:161], v[166:169], v[56:59]
	v_mfma_f32_16x16x32_bf16 v[44:47], v[150:153], v[176:179], v[44:47]
	v_mfma_f32_16x16x32_bf16 v[40:43], v[158:161], v[176:179], v[40:43]
	v_mfma_f32_16x16x32_bf16 v[28:31], v[150:153], v[184:187], v[28:31]
	v_mfma_f32_16x16x32_bf16 v[24:27], v[158:161], v[184:187], v[24:27]
	v_mfma_f32_16x16x32_bf16 v[12:15], v[150:153], v[194:197], v[12:15]
	v_mfma_f32_16x16x32_bf16 v[8:11], v[158:161], v[194:197], v[8:11]
	s_setprio 0
	s_barrier
	s_add_u32 s50, s50, 0x80080
	s_addc_u32 s51, s51, 0
	s_add_i32 s52, s52, s39
	v_lshl_add_u64 v[142:143], s[50:51], 0, v[128:129]
	s_mov_b32 m0, s52
	s_nop 0
	global_load_lds_dwordx4 v[142:143], off
	v_lshl_add_u64 v[142:143], s[50:51], 0, v[134:135]
	s_add_i32 m0, s52, 0x2000
	s_nop 0
	global_load_lds_dwordx4 v[142:143], off
	s_waitcnt vmcnt(6)
	s_barrier
	s_setprio 1
	v_mfma_f32_16x16x32_bf16 v[52:55], v[198:201], v[162:165], v[52:55]
	v_mfma_f32_16x16x32_bf16 v[48:51], v[206:209], v[162:165], v[48:51]
	v_mfma_f32_16x16x32_bf16 v[36:39], v[198:201], v[170:173], v[36:39]
	v_mfma_f32_16x16x32_bf16 v[32:35], v[206:209], v[170:173], v[32:35]
	v_mfma_f32_16x16x32_bf16 v[20:23], v[198:201], v[180:183], v[20:23]
	v_mfma_f32_16x16x32_bf16 v[16:19], v[206:209], v[180:183], v[16:19]
	v_mfma_f32_16x16x32_bf16 v[4:7], v[198:201], v[188:191], v[4:7]
	v_mfma_f32_16x16x32_bf16 v[0:3], v[206:209], v[188:191], v[0:3]
	v_mfma_f32_16x16x32_bf16 v[52:55], v[202:205], v[166:169], v[52:55]
	v_mfma_f32_16x16x32_bf16 v[48:51], v[210:213], v[166:169], v[48:51]
	v_mfma_f32_16x16x32_bf16 v[36:39], v[202:205], v[176:179], v[36:39]
	v_mfma_f32_16x16x32_bf16 v[32:35], v[210:213], v[176:179], v[32:35]
	v_mfma_f32_16x16x32_bf16 v[20:23], v[202:205], v[184:187], v[20:23]
	v_mfma_f32_16x16x32_bf16 v[16:19], v[210:213], v[184:187], v[16:19]
	v_mfma_f32_16x16x32_bf16 v[4:7], v[202:205], v[194:197], v[4:7]
	v_mfma_f32_16x16x32_bf16 v[0:3], v[210:213], v[194:197], v[0:3]
	s_setprio 0
	s_add_i32 s75, s75, 2
	s_add_u32 s2, s2, 0x100
	s_addc_u32 s3, s3, 0
	s_add_u32 s73, s73, 0x100
	s_addc_u32 s74, s74, 0
	s_cmp_gt_u32 s75, 29
	s_barrier
	s_cbranch_scc0 .LBB0_670
	v_and_b32_e32 v149, 64, v174
	v_xor_b32_e32 v145, 16, v174
	v_add_u32_e32 v149, 64, v149
	v_cmp_lt_i32_e32 vcc, v145, v149
	v_lshl_add_u32 v144, s67, 8, v146
	s_lshl_b32 s2, s70, 8
	v_cndmask_b32_e32 v145, v174, v145, vcc
	v_lshlrev_b32_e32 v150, 2, v145
	v_xor_b32_e32 v145, 32, v174
	v_cmp_lt_i32_e32 vcc, v145, v149
	s_ashr_i32 s3, s2, 31
	v_mov_b32_e32 v143, s3
	v_cndmask_b32_e32 v145, v174, v145, vcc
	v_lshlrev_b32_e32 v149, 2, v145
	v_ashrrev_i32_e32 v145, 31, v144
	v_or_b32_e32 v142, s2, v136
	v_lshlrev_b64 v[152:153], 10, v[144:145]
	v_readlane_b32 s0, v246, 53
	v_lshl_add_u64 v[156:157], v[152:153], 0, v[142:143]
	v_readlane_b32 s1, v246, 54
	v_readlane_b32 s2, v246, 55
	v_readlane_b32 s3, v246, 56
	v_lshl_add_u64 v[158:159], v[156:157], 2, s[0:1]
	global_load_dwordx4 v[160:163], v[158:159], off
	global_load_dwordx4 v[164:167], v[158:159], off offset:64
	global_load_dwordx4 v[168:171], v[158:159], off offset:512
	global_load_dwordx4 v[176:179], v[158:159], off offset:576
	v_add_co_u32_e32 v214, vcc, 0x10000, v158
	s_nop 1
	v_addc_co_u32_e32 v215, vcc, 0, v159, vcc
	global_load_dwordx4 v[180:183], v[214:215], off
	global_load_dwordx4 v[184:187], v[214:215], off offset:64
	global_load_dwordx4 v[188:191], v[214:215], off offset:512
	global_load_dwordx4 v[194:197], v[214:215], off offset:576
	v_add_co_u32_e32 v214, vcc, 0x20000, v158
	s_nop 1
	v_addc_co_u32_e32 v215, vcc, 0, v159, vcc
	global_load_dwordx4 v[198:201], v[214:215], off
	global_load_dwordx4 v[202:205], v[214:215], off offset:64
	global_load_dwordx4 v[206:209], v[214:215], off offset:512
	global_load_dwordx4 v[210:213], v[214:215], off offset:576
	s_waitcnt vmcnt(8)
	v_pk_add_f32 v[124:125], v[124:125], v[160:161]
	v_pk_add_f32 v[126:127], v[126:127], v[162:163]
	v_pk_add_f32 v[120:121], v[120:121], v[164:165]
	v_pk_add_f32 v[122:123], v[122:123], v[166:167]
	v_pk_add_f32 v[116:117], v[116:117], v[168:169]
	v_pk_add_f32 v[118:119], v[118:119], v[170:171]
	v_pk_add_f32 v[112:113], v[112:113], v[176:177]
	v_pk_add_f32 v[114:115], v[114:115], v[178:179]
	v_add_co_u32_e32 v214, vcc, 0x30000, v158
	s_nop 1
	v_addc_co_u32_e32 v215, vcc, 0, v159, vcc
	global_load_dwordx4 v[160:163], v[214:215], off
	global_load_dwordx4 v[164:167], v[214:215], off offset:64
	global_load_dwordx4 v[168:171], v[214:215], off offset:512
	global_load_dwordx4 v[176:179], v[214:215], off offset:576
	s_waitcnt vmcnt(8)
	v_pk_add_f32 v[108:109], v[108:109], v[180:181]
	v_pk_add_f32 v[110:111], v[110:111], v[182:183]
	v_pk_add_f32 v[104:105], v[104:105], v[184:185]
	v_pk_add_f32 v[106:107], v[106:107], v[186:187]
	v_pk_add_f32 v[100:101], v[100:101], v[188:189]
	v_pk_add_f32 v[102:103], v[102:103], v[190:191]
	v_pk_add_f32 v[96:97], v[96:97], v[194:195]
	v_pk_add_f32 v[98:99], v[98:99], v[196:197]
	v_add_co_u32_e32 v214, vcc, 0x80000, v158
	s_nop 1
	v_addc_co_u32_e32 v215, vcc, 0, v159, vcc
	global_load_dwordx4 v[180:183], v[214:215], off
	global_load_dwordx4 v[184:187], v[214:215], off offset:64
	global_load_dwordx4 v[188:191], v[214:215], off offset:512
	global_load_dwordx4 v[194:197], v[214:215], off offset:576
	s_waitcnt vmcnt(8)
; DI unsigned pk2(float a, float b) { f32x2 v = {a, b}; bf2_t r = __builtin_convertvector(v, bf2_t); return __builtin_bit_cast(unsigned, r); }
; __global__ void __launch_bounds__(512) hybrid_fwd(Params p) {
;     ...
;           [=](const f32x4 (&acc)[2][2][4][2], int pm, int pn, int wr, int wc, int fr, int fq) {
; #pragma unroll
;               for (int ai = 0; ai < 2; ++ai)
; #pragma unroll
;                   for (int m = 0; m < 4; ++m) { const int row = pm * 256 + ai * 128 + wr * 64 + m * 16 + fr; const size_t ro = (size_t)row * 1024 + pn * 256 + wc * 32 + 4 * fq;
;                       float ssq = 0.f;
; #pragma unroll
;                       for (int bj = 0; bj < 2; ++bj)
; #pragma unroll
;                           for (int n = 0; n < 2; ++n) { const size_t o = ro + bj * 128 + n * 16; const f32x4 v = *(const f32x4*)(X + o) + acc[ai][bj][m][n];
;                               u32x2 wv; wv[0] = pk2(v[0], v[1]); wv[1] = pk2(v[2], v[3]); *(u32x2*)(U + o) = wv;
;                               ssq += v[0] * v[0] + v[1] * v[1] + v[2] * v[2] + v[3] * v[3]; }
;                       ssq += __shfl_xor(ssq, 16); ssq += __shfl_xor(ssq, 32);
;                       if (fq == 0) unsafeAtomicAdd(SS1 + row, ssq); } }, vb); }
	v_pk_add_f32 v[92:93], v[92:93], v[198:199]
	v_pk_add_f32 v[94:95], v[94:95], v[200:201]
	v_pk_add_f32 v[88:89], v[88:89], v[202:203]
	v_pk_add_f32 v[90:91], v[90:91], v[204:205]
	v_pk_add_f32 v[84:85], v[84:85], v[206:207]
	v_pk_add_f32 v[86:87], v[86:87], v[208:209]
	v_pk_add_f32 v[80:81], v[80:81], v[210:211]
	v_pk_add_f32 v[82:83], v[82:83], v[212:213]
	v_add_co_u32_e32 v214, vcc, 0x90000, v158
	s_nop 1
	v_addc_co_u32_e32 v215, vcc, 0, v159, vcc
	global_load_dwordx4 v[198:201], v[214:215], off
	global_load_dwordx4 v[202:205], v[214:215], off offset:64
	global_load_dwordx4 v[206:209], v[214:215], off offset:512
	global_load_dwordx4 v[210:213], v[214:215], off offset:576
	s_waitcnt vmcnt(8)
	v_pk_add_f32 v[76:77], v[76:77], v[160:161]
	v_pk_add_f32 v[78:79], v[78:79], v[162:163]
	v_pk_add_f32 v[72:73], v[72:73], v[164:165]
	v_pk_add_f32 v[74:75], v[74:75], v[166:167]
	v_pk_add_f32 v[68:69], v[68:69], v[168:169]
	v_pk_add_f32 v[70:71], v[70:71], v[170:171]
	v_pk_add_f32 v[64:65], v[64:65], v[176:177]
	v_pk_add_f32 v[66:67], v[66:67], v[178:179]
	v_add_co_u32_e32 v214, vcc, 0xa0000, v158
	s_nop 1
	v_addc_co_u32_e32 v215, vcc, 0, v159, vcc
	global_load_dwordx4 v[160:163], v[214:215], off
	global_load_dwordx4 v[164:167], v[214:215], off offset:64
	global_load_dwordx4 v[168:171], v[214:215], off offset:512
	global_load_dwordx4 v[176:179], v[214:215], off offset:576
	s_waitcnt vmcnt(8)
	v_pk_add_f32 v[60:61], v[60:61], v[180:181]
	v_pk_add_f32 v[62:63], v[62:63], v[182:183]
	v_pk_add_f32 v[56:57], v[56:57], v[184:185]
	v_pk_add_f32 v[58:59], v[58:59], v[186:187]
	v_pk_add_f32 v[52:53], v[52:53], v[188:189]
	v_pk_add_f32 v[54:55], v[54:55], v[190:191]
	v_pk_add_f32 v[48:49], v[48:49], v[194:195]
	v_pk_add_f32 v[50:51], v[50:51], v[196:197]
	v_add_co_u32_e32 v214, vcc, 0xb0000, v158
	s_nop 1
	v_addc_co_u32_e32 v215, vcc, 0, v159, vcc
	global_load_dwordx4 v[180:183], v[214:215], off
	global_load_dwordx4 v[184:187], v[214:215], off offset:64
	global_load_dwordx4 v[188:191], v[214:215], off offset:512
	global_load_dwordx4 v[194:197], v[214:215], off offset:576
	s_waitcnt vmcnt(8)
	v_pk_add_f32 v[44:45], v[44:45], v[198:199]
	v_pk_add_f32 v[46:47], v[46:47], v[200:201]
	v_pk_add_f32 v[40:41], v[40:41], v[202:203]
	v_pk_add_f32 v[42:43], v[42:43], v[204:205]
	v_pk_add_f32 v[36:37], v[36:37], v[206:207]
	v_pk_add_f32 v[38:39], v[38:39], v[208:209]
	v_pk_add_f32 v[32:33], v[32:33], v[210:211]
	v_pk_add_f32 v[34:35], v[34:35], v[212:213]
	s_waitcnt vmcnt(4)
	v_pk_add_f32 v[28:29], v[28:29], v[160:161]
	v_pk_add_f32 v[30:31], v[30:31], v[162:163]
	v_pk_add_f32 v[24:25], v[24:25], v[164:165]
	v_pk_add_f32 v[26:27], v[26:27], v[166:167]
	v_pk_add_f32 v[20:21], v[20:21], v[168:169]
	v_pk_add_f32 v[22:23], v[22:23], v[170:171]
	v_pk_add_f32 v[16:17], v[16:17], v[176:177]
	v_pk_add_f32 v[18:19], v[18:19], v[178:179]
	s_waitcnt vmcnt(0)
	v_pk_add_f32 v[12:13], v[12:13], v[180:181]
	v_pk_add_f32 v[14:15], v[14:15], v[182:183]
	v_pk_add_f32 v[8:9], v[8:9], v[184:185]
	v_pk_add_f32 v[10:11], v[10:11], v[186:187]
	v_pk_add_f32 v[4:5], v[4:5], v[188:189]
	v_pk_add_f32 v[6:7], v[6:7], v[190:191]
	v_pk_add_f32 v[0:1], v[0:1], v[194:195]
	v_pk_add_f32 v[2:3], v[2:3], v[196:197]
	v_readlane_b32 s4, v246, 57
	v_readlane_b32 s5, v246, 58
	v_readlane_b32 s6, v246, 59
	v_readlane_b32 s7, v246, 60
	v_readlane_b32 s8, v246, 61
	v_readlane_b32 s9, v246, 62
	v_readlane_b32 s10, v246, 63
	v_readlane_b32 s11, v245, 0
	v_readlane_b32 s12, v245, 1
	v_readlane_b32 s13, v245, 2
	v_readlane_b32 s14, v245, 3
	v_readlane_b32 s15, v245, 4
	v_lshlrev_b64 v[154:155], 1, v[156:157]
	v_mul_f32_e32 v151, v125, v125
	v_cvt_pk_bf16_f32 v152, v124, v125
	v_cvt_pk_bf16_f32 v153, v126, v127
	v_lshl_add_u64 v[156:157], s[20:21], 0, v[154:155]
	v_fmac_f32_e32 v151, v124, v124
	global_store_dwordx2 v[156:157], v[152:153], off
	v_fmac_f32_e32 v151, v126, v126
	v_fmac_f32_e32 v151, v127, v127
	s_nop 0
	v_cvt_pk_bf16_f32 v124, v120, v121
	v_mul_f32_e32 v121, v121, v121
	v_or_b32_e32 v126, 32, v154
	v_mov_b32_e32 v127, v155
	v_fmac_f32_e32 v121, v120, v120
	v_cvt_pk_bf16_f32 v125, v122, v123
	v_lshl_add_u64 v[126:127], s[20:21], 0, v[126:127]
	v_fmac_f32_e32 v121, v122, v122
	global_store_dwordx2 v[126:127], v[124:125], off
	v_fmac_f32_e32 v121, v123, v123
	v_add_f32_e32 v124, v151, v121
	s_nop 0
	v_cvt_pk_bf16_f32 v120, v116, v117
	v_mul_f32_e32 v117, v117, v117
	v_or_b32_e32 v122, 0x100, v154
	v_mov_b32_e32 v123, v155
	v_fmac_f32_e32 v117, v116, v116
	v_cvt_pk_bf16_f32 v121, v118, v119
	v_lshl_add_u64 v[122:123], s[20:21], 0, v[122:123]
	v_fmac_f32_e32 v117, v118, v118
	global_store_dwordx2 v[122:123], v[120:121], off
	v_fmac_f32_e32 v117, v119, v119
	v_add_f32_e32 v120, v124, v117
	v_or_b32_e32 v154, 0x120, v154
	s_nop 0
	v_cvt_pk_bf16_f32 v116, v112, v113
	v_mul_f32_e32 v113, v113, v113
	v_fmac_f32_e32 v113, v112, v112
	v_fmac_f32_e32 v113, v114, v114
	v_fmac_f32_e32 v113, v115, v115
	v_add_f32_e32 v112, v120, v113
	ds_bpermute_b32 v113, v150, v112
	v_cvt_pk_bf16_f32 v117, v114, v115
	v_lshl_add_u64 v[118:119], s[20:21], 0, v[154:155]
	global_store_dwordx2 v[118:119], v[116:117], off
	s_waitcnt lgkmcnt(0)
	v_add_f32_e32 v112, v112, v113
	ds_bpermute_b32 v113, v149, v112
	s_and_saveexec_b64 s[2:3], s[42:43]
	s_cbranch_execz .LBB0_673
	v_lshl_add_u64 v[114:115], v[144:145], 2, s[86:87]
	s_waitcnt lgkmcnt(0)
	v_add_f32_e32 v112, v112, v113
	global_atomic_add_f32 v[114:115], v112, off
; DI unsigned pk2(float a, float b) { f32x2 v = {a, b}; bf2_t r = __builtin_convertvector(v, bf2_t); return __builtin_bit_cast(unsigned, r); }
; __global__ void __launch_bounds__(512) hybrid_fwd(Params p) {
;     ...
;                   for (int m = 0; m < 4; ++m) { const int row = pm * 256 + ai * 128 + wr * 64 + m * 16 + fr; const size_t ro = (size_t)row * 1024 + pn * 256 + wc * 32 + 4 * fq;
;                       float ssq = 0.f;
; #pragma unroll
;                       for (int bj = 0; bj < 2; ++bj)
; #pragma unroll
;                           for (int n = 0; n < 2; ++n) { const size_t o = ro + bj * 128 + n * 16; const f32x4 v = *(const f32x4*)(X + o) + acc[ai][bj][m][n];
;                               u32x2 wv; wv[0] = pk2(v[0], v[1]); wv[1] = pk2(v[2], v[3]); *(u32x2*)(U + o) = wv;
;                               ssq += v[0] * v[0] + v[1] * v[1] + v[2] * v[2] + v[3] * v[3]; }
;                       ssq += __shfl_xor(ssq, 16); ssq += __shfl_xor(ssq, 32);
;                       if (fq == 0) unsafeAtomicAdd(SS1 + row, ssq); } }, vb); }
.LBB0_673:
	s_or_b64 exec, exec, s[2:3]
	v_or_b32_e32 v112, 16, v144
	s_waitcnt lgkmcnt(0)
	v_ashrrev_i32_e32 v113, 31, v112
	v_lshlrev_b64 v[114:115], 10, v[112:113]
	v_readlane_b32 s0, v246, 53
	v_lshl_add_u64 v[118:119], v[114:115], 0, v[142:143]
	v_readlane_b32 s1, v246, 54
	v_readlane_b32 s2, v246, 55
	v_readlane_b32 s3, v246, 56
	v_lshl_add_u64 v[120:121], v[118:119], 2, s[0:1]
	v_readlane_b32 s4, v246, 57
	v_readlane_b32 s5, v246, 58
	v_readlane_b32 s6, v246, 59
	v_readlane_b32 s7, v246, 60
	v_readlane_b32 s8, v246, 61
	v_readlane_b32 s9, v246, 62
	v_readlane_b32 s10, v246, 63
	v_readlane_b32 s11, v245, 0
	v_readlane_b32 s12, v245, 1
	v_readlane_b32 s13, v245, 2
	v_readlane_b32 s14, v245, 3
	v_readlane_b32 s15, v245, 4
	v_lshlrev_b64 v[116:117], 1, v[118:119]
	v_cvt_pk_bf16_f32 v114, v108, v109
	v_cvt_pk_bf16_f32 v115, v110, v111
	v_lshl_add_u64 v[118:119], s[20:21], 0, v[116:117]
	global_store_dwordx2 v[118:119], v[114:115], off
	v_mul_f32_e32 v114, v109, v109
	v_fmac_f32_e32 v114, v108, v108
	v_fmac_f32_e32 v114, v110, v110
	v_fmac_f32_e32 v114, v111, v111
	s_nop 0
	v_cvt_pk_bf16_f32 v108, v104, v105
	v_mul_f32_e32 v105, v105, v105
	v_or_b32_e32 v110, 32, v116
	v_mov_b32_e32 v111, v117
	v_fmac_f32_e32 v105, v104, v104
	v_cvt_pk_bf16_f32 v109, v106, v107
	v_lshl_add_u64 v[110:111], s[20:21], 0, v[110:111]
	v_fmac_f32_e32 v105, v106, v106
	global_store_dwordx2 v[110:111], v[108:109], off
	v_fmac_f32_e32 v105, v107, v107
	v_add_f32_e32 v108, v114, v105
	s_nop 0
	v_cvt_pk_bf16_f32 v104, v100, v101
	v_mul_f32_e32 v101, v101, v101
	v_or_b32_e32 v106, 0x100, v116
	v_mov_b32_e32 v107, v117
	v_fmac_f32_e32 v101, v100, v100
	v_cvt_pk_bf16_f32 v105, v102, v103
	v_lshl_add_u64 v[106:107], s[20:21], 0, v[106:107]
	v_fmac_f32_e32 v101, v102, v102
	global_store_dwordx2 v[106:107], v[104:105], off
	v_fmac_f32_e32 v101, v103, v103
	v_add_f32_e32 v104, v108, v101
	v_or_b32_e32 v116, 0x120, v116
	s_nop 0
	v_cvt_pk_bf16_f32 v100, v96, v97
	v_mul_f32_e32 v97, v97, v97
	v_fmac_f32_e32 v97, v96, v96
	v_fmac_f32_e32 v97, v98, v98
	v_fmac_f32_e32 v97, v99, v99
	v_add_f32_e32 v96, v104, v97
	ds_bpermute_b32 v97, v150, v96
	v_cvt_pk_bf16_f32 v101, v98, v99
	v_lshl_add_u64 v[102:103], s[20:21], 0, v[116:117]
	global_store_dwordx2 v[102:103], v[100:101], off
	s_waitcnt lgkmcnt(0)
	v_add_f32_e32 v96, v96, v97
	ds_bpermute_b32 v97, v149, v96
	s_and_saveexec_b64 s[2:3], s[42:43]
	s_cbranch_execz .LBB0_675
	v_lshl_add_u64 v[98:99], v[112:113], 2, s[86:87]
	s_waitcnt lgkmcnt(0)
	v_add_f32_e32 v96, v96, v97
	global_atomic_add_f32 v[98:99], v96, off
.LBB0_675:
	s_or_b64 exec, exec, s[2:3]
	v_or_b32_e32 v96, 32, v144
	s_waitcnt lgkmcnt(0)
	v_ashrrev_i32_e32 v97, 31, v96
	v_lshlrev_b64 v[98:99], 10, v[96:97]
	v_readlane_b32 s0, v246, 53
	v_lshl_add_u64 v[102:103], v[98:99], 0, v[142:143]
	v_readlane_b32 s1, v246, 54
	v_readlane_b32 s2, v246, 55
	v_readlane_b32 s3, v246, 56
	v_lshl_add_u64 v[104:105], v[102:103], 2, s[0:1]
	v_readlane_b32 s4, v246, 57
	v_readlane_b32 s5, v246, 58
	v_readlane_b32 s6, v246, 59
	v_readlane_b32 s7, v246, 60
	v_readlane_b32 s8, v246, 61
	v_readlane_b32 s9, v246, 62
	v_readlane_b32 s10, v246, 63
	v_readlane_b32 s11, v245, 0
	v_readlane_b32 s12, v245, 1
	v_readlane_b32 s13, v245, 2
	v_readlane_b32 s14, v245, 3
	v_readlane_b32 s15, v245, 4
	v_lshlrev_b64 v[100:101], 1, v[102:103]
	v_cvt_pk_bf16_f32 v98, v92, v93
	v_cvt_pk_bf16_f32 v99, v94, v95
	v_lshl_add_u64 v[102:103], s[20:21], 0, v[100:101]
	global_store_dwordx2 v[102:103], v[98:99], off
	v_mul_f32_e32 v98, v93, v93
	v_fmac_f32_e32 v98, v92, v92
	v_fmac_f32_e32 v98, v94, v94
	v_fmac_f32_e32 v98, v95, v95
	s_nop 0
	v_cvt_pk_bf16_f32 v92, v88, v89
	v_mul_f32_e32 v89, v89, v89
	v_or_b32_e32 v94, 32, v100
	v_mov_b32_e32 v95, v101
	v_fmac_f32_e32 v89, v88, v88
	v_cvt_pk_bf16_f32 v93, v90, v91
	v_lshl_add_u64 v[94:95], s[20:21], 0, v[94:95]
	v_fmac_f32_e32 v89, v90, v90
	global_store_dwordx2 v[94:95], v[92:93], off
	v_fmac_f32_e32 v89, v91, v91
	v_add_f32_e32 v92, v98, v89
	s_nop 0
	v_cvt_pk_bf16_f32 v88, v84, v85
	v_mul_f32_e32 v85, v85, v85
	v_or_b32_e32 v90, 0x100, v100
	v_mov_b32_e32 v91, v101
	v_fmac_f32_e32 v85, v84, v84
	v_cvt_pk_bf16_f32 v89, v86, v87
	v_lshl_add_u64 v[90:91], s[20:21], 0, v[90:91]
	v_fmac_f32_e32 v85, v86, v86
	global_store_dwordx2 v[90:91], v[88:89], off
	v_fmac_f32_e32 v85, v87, v87
	v_add_f32_e32 v88, v92, v85
	v_or_b32_e32 v100, 0x120, v100
	s_nop 0
	v_cvt_pk_bf16_f32 v84, v80, v81
	v_mul_f32_e32 v81, v81, v81
	v_fmac_f32_e32 v81, v80, v80
	v_fmac_f32_e32 v81, v82, v82
	v_fmac_f32_e32 v81, v83, v83
	v_add_f32_e32 v80, v88, v81
	ds_bpermute_b32 v81, v150, v80
	v_cvt_pk_bf16_f32 v85, v82, v83
	v_lshl_add_u64 v[86:87], s[20:21], 0, v[100:101]
	global_store_dwordx2 v[86:87], v[84:85], off
	s_waitcnt lgkmcnt(0)
	v_add_f32_e32 v80, v80, v81
	ds_bpermute_b32 v81, v149, v80
	s_and_saveexec_b64 s[2:3], s[42:43]
	s_cbranch_execz .LBB0_677
	v_lshl_add_u64 v[82:83], v[96:97], 2, s[86:87]
	s_waitcnt lgkmcnt(0)
	v_add_f32_e32 v80, v80, v81
	global_atomic_add_f32 v[82:83], v80, off
; DI unsigned pk2(float a, float b) { f32x2 v = {a, b}; bf2_t r = __builtin_convertvector(v, bf2_t); return __builtin_bit_cast(unsigned, r); }
; __global__ void __launch_bounds__(512) hybrid_fwd(Params p) {
;     ...
;                   for (int m = 0; m < 4; ++m) { const int row = pm * 256 + ai * 128 + wr * 64 + m * 16 + fr; const size_t ro = (size_t)row * 1024 + pn * 256 + wc * 32 + 4 * fq;
;                       float ssq = 0.f;
; #pragma unroll
;                       for (int bj = 0; bj < 2; ++bj)
; #pragma unroll
;                           for (int n = 0; n < 2; ++n) { const size_t o = ro + bj * 128 + n * 16; const f32x4 v = *(const f32x4*)(X + o) + acc[ai][bj][m][n];
;                               u32x2 wv; wv[0] = pk2(v[0], v[1]); wv[1] = pk2(v[2], v[3]); *(u32x2*)(U + o) = wv;
;                               ssq += v[0] * v[0] + v[1] * v[1] + v[2] * v[2] + v[3] * v[3]; }
;                       ssq += __shfl_xor(ssq, 16); ssq += __shfl_xor(ssq, 32);
;                       if (fq == 0) unsafeAtomicAdd(SS1 + row, ssq); } }, vb); }
.LBB0_677:
	s_or_b64 exec, exec, s[2:3]
	v_or_b32_e32 v80, 48, v144
	s_waitcnt lgkmcnt(0)
	v_ashrrev_i32_e32 v81, 31, v80
	v_lshlrev_b64 v[82:83], 10, v[80:81]
	v_readlane_b32 s0, v246, 53
	v_lshl_add_u64 v[86:87], v[82:83], 0, v[142:143]
	v_readlane_b32 s1, v246, 54
	v_readlane_b32 s2, v246, 55
	v_readlane_b32 s3, v246, 56
	v_lshl_add_u64 v[88:89], v[86:87], 2, s[0:1]
	v_readlane_b32 s4, v246, 57
	v_readlane_b32 s5, v246, 58
	v_readlane_b32 s6, v246, 59
	v_readlane_b32 s7, v246, 60
	v_readlane_b32 s8, v246, 61
	v_readlane_b32 s9, v246, 62
	v_readlane_b32 s10, v246, 63
	v_readlane_b32 s11, v245, 0
	v_readlane_b32 s12, v245, 1
	v_readlane_b32 s13, v245, 2
	v_readlane_b32 s14, v245, 3
	v_readlane_b32 s15, v245, 4
	v_lshlrev_b64 v[84:85], 1, v[86:87]
	v_cvt_pk_bf16_f32 v82, v76, v77
	v_cvt_pk_bf16_f32 v83, v78, v79
	v_lshl_add_u64 v[86:87], s[20:21], 0, v[84:85]
	global_store_dwordx2 v[86:87], v[82:83], off
	v_mul_f32_e32 v82, v77, v77
	v_fmac_f32_e32 v82, v76, v76
	v_fmac_f32_e32 v82, v78, v78
	v_fmac_f32_e32 v82, v79, v79
	s_nop 0
	v_cvt_pk_bf16_f32 v76, v72, v73
	v_mul_f32_e32 v73, v73, v73
	v_or_b32_e32 v78, 32, v84
	v_mov_b32_e32 v79, v85
	v_fmac_f32_e32 v73, v72, v72
	v_cvt_pk_bf16_f32 v77, v74, v75
	v_lshl_add_u64 v[78:79], s[20:21], 0, v[78:79]
	v_fmac_f32_e32 v73, v74, v74
	global_store_dwordx2 v[78:79], v[76:77], off
	v_fmac_f32_e32 v73, v75, v75
	v_add_f32_e32 v76, v82, v73
	s_nop 0
	v_cvt_pk_bf16_f32 v72, v68, v69
	v_mul_f32_e32 v69, v69, v69
	v_or_b32_e32 v74, 0x100, v84
	v_mov_b32_e32 v75, v85
	v_fmac_f32_e32 v69, v68, v68
	v_cvt_pk_bf16_f32 v73, v70, v71
	v_lshl_add_u64 v[74:75], s[20:21], 0, v[74:75]
	v_fmac_f32_e32 v69, v70, v70
	global_store_dwordx2 v[74:75], v[72:73], off
	v_fmac_f32_e32 v69, v71, v71
	v_add_f32_e32 v72, v76, v69
	v_or_b32_e32 v84, 0x120, v84
	s_nop 0
	v_cvt_pk_bf16_f32 v68, v64, v65
	v_mul_f32_e32 v65, v65, v65
	v_fmac_f32_e32 v65, v64, v64
	v_fmac_f32_e32 v65, v66, v66
	v_fmac_f32_e32 v65, v67, v67
	v_add_f32_e32 v64, v72, v65
	ds_bpermute_b32 v65, v150, v64
	v_cvt_pk_bf16_f32 v69, v66, v67
	v_lshl_add_u64 v[70:71], s[20:21], 0, v[84:85]
	global_store_dwordx2 v[70:71], v[68:69], off
	s_waitcnt lgkmcnt(0)
	v_add_f32_e32 v64, v64, v65
	ds_bpermute_b32 v65, v149, v64
	s_and_saveexec_b64 s[2:3], s[42:43]
	s_cbranch_execz .LBB0_679
	v_lshl_add_u64 v[66:67], v[80:81], 2, s[86:87]
	s_waitcnt lgkmcnt(0)
	v_add_f32_e32 v64, v64, v65
	global_atomic_add_f32 v[66:67], v64, off
.LBB0_679:
	s_or_b64 exec, exec, s[2:3]
	v_add_u32_e32 v64, 0x80, v144
	s_waitcnt lgkmcnt(0)
	v_ashrrev_i32_e32 v65, 31, v64
	v_lshlrev_b64 v[66:67], 10, v[64:65]
	v_readlane_b32 s0, v246, 53
	v_lshl_add_u64 v[70:71], v[66:67], 0, v[142:143]
	v_readlane_b32 s1, v246, 54
	v_readlane_b32 s2, v246, 55
	v_readlane_b32 s3, v246, 56
	v_lshl_add_u64 v[72:73], v[70:71], 2, s[0:1]
	v_readlane_b32 s4, v246, 57
	v_readlane_b32 s5, v246, 58
	v_readlane_b32 s6, v246, 59
	v_readlane_b32 s7, v246, 60
	v_readlane_b32 s8, v246, 61
	v_readlane_b32 s9, v246, 62
	v_readlane_b32 s10, v246, 63
	v_readlane_b32 s11, v245, 0
	v_readlane_b32 s12, v245, 1
	v_readlane_b32 s13, v245, 2
	v_readlane_b32 s14, v245, 3
	v_readlane_b32 s15, v245, 4
	v_lshlrev_b64 v[68:69], 1, v[70:71]
	v_cvt_pk_bf16_f32 v66, v60, v61
	v_cvt_pk_bf16_f32 v67, v62, v63
	v_lshl_add_u64 v[70:71], s[20:21], 0, v[68:69]
	global_store_dwordx2 v[70:71], v[66:67], off
	v_mul_f32_e32 v66, v61, v61
	v_fmac_f32_e32 v66, v60, v60
	v_fmac_f32_e32 v66, v62, v62
	v_fmac_f32_e32 v66, v63, v63
	s_nop 0
	v_cvt_pk_bf16_f32 v60, v56, v57
	v_mul_f32_e32 v57, v57, v57
	v_or_b32_e32 v62, 32, v68
	v_mov_b32_e32 v63, v69
	v_fmac_f32_e32 v57, v56, v56
	v_cvt_pk_bf16_f32 v61, v58, v59
	v_lshl_add_u64 v[62:63], s[20:21], 0, v[62:63]
	v_fmac_f32_e32 v57, v58, v58
	global_store_dwordx2 v[62:63], v[60:61], off
	v_fmac_f32_e32 v57, v59, v59
	v_add_f32_e32 v60, v66, v57
	s_nop 0
	v_cvt_pk_bf16_f32 v56, v52, v53
	v_mul_f32_e32 v53, v53, v53
	v_or_b32_e32 v58, 0x100, v68
	v_mov_b32_e32 v59, v69
	v_fmac_f32_e32 v53, v52, v52
	v_cvt_pk_bf16_f32 v57, v54, v55
	v_lshl_add_u64 v[58:59], s[20:21], 0, v[58:59]
	v_fmac_f32_e32 v53, v54, v54
	global_store_dwordx2 v[58:59], v[56:57], off
	v_fmac_f32_e32 v53, v55, v55
	v_add_f32_e32 v56, v60, v53
	v_or_b32_e32 v68, 0x120, v68
	s_nop 0
	v_cvt_pk_bf16_f32 v52, v48, v49
	v_mul_f32_e32 v49, v49, v49
	v_fmac_f32_e32 v49, v48, v48
	v_fmac_f32_e32 v49, v50, v50
	v_fmac_f32_e32 v49, v51, v51
	v_add_f32_e32 v48, v56, v49
	ds_bpermute_b32 v49, v150, v48
	v_cvt_pk_bf16_f32 v53, v50, v51
	v_lshl_add_u64 v[54:55], s[20:21], 0, v[68:69]
	global_store_dwordx2 v[54:55], v[52:53], off
	s_waitcnt lgkmcnt(0)
	v_add_f32_e32 v48, v48, v49
	ds_bpermute_b32 v49, v149, v48
	s_and_saveexec_b64 s[2:3], s[42:43]
	s_cbranch_execz .LBB0_681
	v_lshl_add_u64 v[50:51], v[64:65], 2, s[86:87]
	s_waitcnt lgkmcnt(0)
	v_add_f32_e32 v48, v48, v49
	global_atomic_add_f32 v[50:51], v48, off
; DI unsigned pk2(float a, float b) { f32x2 v = {a, b}; bf2_t r = __builtin_convertvector(v, bf2_t); return __builtin_bit_cast(unsigned, r); }
; __global__ void __launch_bounds__(512) hybrid_fwd(Params p) {
;     ...
;                   for (int m = 0; m < 4; ++m) { const int row = pm * 256 + ai * 128 + wr * 64 + m * 16 + fr; const size_t ro = (size_t)row * 1024 + pn * 256 + wc * 32 + 4 * fq;
;                       float ssq = 0.f;
; #pragma unroll
;                       for (int bj = 0; bj < 2; ++bj)
; #pragma unroll
;                           for (int n = 0; n < 2; ++n) { const size_t o = ro + bj * 128 + n * 16; const f32x4 v = *(const f32x4*)(X + o) + acc[ai][bj][m][n];
;                               u32x2 wv; wv[0] = pk2(v[0], v[1]); wv[1] = pk2(v[2], v[3]); *(u32x2*)(U + o) = wv;
;                               ssq += v[0] * v[0] + v[1] * v[1] + v[2] * v[2] + v[3] * v[3]; }
;                       ssq += __shfl_xor(ssq, 16); ssq += __shfl_xor(ssq, 32);
;                       if (fq == 0) unsafeAtomicAdd(SS1 + row, ssq); } }, vb); }
.LBB0_681:
	s_or_b64 exec, exec, s[2:3]
	v_add_u32_e32 v48, 0x90, v144
	s_waitcnt lgkmcnt(0)
	v_ashrrev_i32_e32 v49, 31, v48
	v_lshlrev_b64 v[50:51], 10, v[48:49]
	v_readlane_b32 s0, v246, 53
	v_lshl_add_u64 v[54:55], v[50:51], 0, v[142:143]
	v_readlane_b32 s1, v246, 54
	v_readlane_b32 s2, v246, 55
	v_readlane_b32 s3, v246, 56
	v_lshl_add_u64 v[56:57], v[54:55], 2, s[0:1]
	v_readlane_b32 s4, v246, 57
	v_readlane_b32 s5, v246, 58
	v_readlane_b32 s6, v246, 59
	v_readlane_b32 s7, v246, 60
	v_readlane_b32 s8, v246, 61
	v_readlane_b32 s9, v246, 62
	v_readlane_b32 s10, v246, 63
	v_readlane_b32 s11, v245, 0
	v_readlane_b32 s12, v245, 1
	v_readlane_b32 s13, v245, 2
	v_readlane_b32 s14, v245, 3
	v_readlane_b32 s15, v245, 4
	v_lshlrev_b64 v[52:53], 1, v[54:55]
	v_cvt_pk_bf16_f32 v50, v44, v45
	v_cvt_pk_bf16_f32 v51, v46, v47
	v_lshl_add_u64 v[54:55], s[20:21], 0, v[52:53]
	global_store_dwordx2 v[54:55], v[50:51], off
	v_mul_f32_e32 v50, v45, v45
	v_fmac_f32_e32 v50, v44, v44
	v_fmac_f32_e32 v50, v46, v46
	v_fmac_f32_e32 v50, v47, v47
	s_nop 0
	v_cvt_pk_bf16_f32 v44, v40, v41
	v_mul_f32_e32 v41, v41, v41
	v_or_b32_e32 v46, 32, v52
	v_mov_b32_e32 v47, v53
	v_fmac_f32_e32 v41, v40, v40
	v_cvt_pk_bf16_f32 v45, v42, v43
	v_lshl_add_u64 v[46:47], s[20:21], 0, v[46:47]
	v_fmac_f32_e32 v41, v42, v42
	global_store_dwordx2 v[46:47], v[44:45], off
	v_fmac_f32_e32 v41, v43, v43
	v_add_f32_e32 v44, v50, v41
	s_nop 0
	v_cvt_pk_bf16_f32 v40, v36, v37
	v_mul_f32_e32 v37, v37, v37
	v_or_b32_e32 v42, 0x100, v52
	v_mov_b32_e32 v43, v53
	v_fmac_f32_e32 v37, v36, v36
	v_cvt_pk_bf16_f32 v41, v38, v39
	v_lshl_add_u64 v[42:43], s[20:21], 0, v[42:43]
	v_fmac_f32_e32 v37, v38, v38
	global_store_dwordx2 v[42:43], v[40:41], off
	v_fmac_f32_e32 v37, v39, v39
	v_add_f32_e32 v40, v44, v37
	v_or_b32_e32 v52, 0x120, v52
	s_nop 0
	v_cvt_pk_bf16_f32 v36, v32, v33
	v_mul_f32_e32 v33, v33, v33
	v_fmac_f32_e32 v33, v32, v32
	v_fmac_f32_e32 v33, v34, v34
	v_fmac_f32_e32 v33, v35, v35
	v_add_f32_e32 v32, v40, v33
	ds_bpermute_b32 v33, v150, v32
	v_cvt_pk_bf16_f32 v37, v34, v35
	v_lshl_add_u64 v[38:39], s[20:21], 0, v[52:53]
	global_store_dwordx2 v[38:39], v[36:37], off
	s_waitcnt lgkmcnt(0)
	v_add_f32_e32 v32, v32, v33
	ds_bpermute_b32 v33, v149, v32
	s_and_saveexec_b64 s[2:3], s[42:43]
	s_cbranch_execz .LBB0_683
	v_lshl_add_u64 v[34:35], v[48:49], 2, s[86:87]
	s_waitcnt lgkmcnt(0)
	v_add_f32_e32 v32, v32, v33
	global_atomic_add_f32 v[34:35], v32, off
; DI unsigned pk2(float a, float b) { f32x2 v = {a, b}; bf2_t r = __builtin_convertvector(v, bf2_t); return __builtin_bit_cast(unsigned, r); }
; __global__ void __launch_bounds__(512) hybrid_fwd(Params p) {
;     ...
;                   for (int m = 0; m < 4; ++m) { const int row = pm * 256 + ai * 128 + wr * 64 + m * 16 + fr; const size_t ro = (size_t)row * 1024 + pn * 256 + wc * 32 + 4 * fq;
;                       float ssq = 0.f;
; #pragma unroll
;                       for (int bj = 0; bj < 2; ++bj)
; #pragma unroll
;                           for (int n = 0; n < 2; ++n) { const size_t o = ro + bj * 128 + n * 16; const f32x4 v = *(const f32x4*)(X + o) + acc[ai][bj][m][n];
;                               u32x2 wv; wv[0] = pk2(v[0], v[1]); wv[1] = pk2(v[2], v[3]); *(u32x2*)(U + o) = wv;
;                               ssq += v[0] * v[0] + v[1] * v[1] + v[2] * v[2] + v[3] * v[3]; }
;                       ssq += __shfl_xor(ssq, 16); ssq += __shfl_xor(ssq, 32);
;                       if (fq == 0) unsafeAtomicAdd(SS1 + row, ssq); } }, vb); }
.LBB0_683:
	s_or_b64 exec, exec, s[2:3]
	v_add_u32_e32 v32, 0xa0, v144
	s_waitcnt lgkmcnt(0)
	v_ashrrev_i32_e32 v33, 31, v32
	v_lshlrev_b64 v[34:35], 10, v[32:33]
	v_readlane_b32 s0, v246, 53
	v_lshl_add_u64 v[38:39], v[34:35], 0, v[142:143]
	v_readlane_b32 s1, v246, 54
	v_readlane_b32 s2, v246, 55
	v_readlane_b32 s3, v246, 56
	v_lshl_add_u64 v[40:41], v[38:39], 2, s[0:1]
	v_readlane_b32 s4, v246, 57
	v_readlane_b32 s5, v246, 58
	v_readlane_b32 s6, v246, 59
	v_readlane_b32 s7, v246, 60
	v_readlane_b32 s8, v246, 61
	v_readlane_b32 s9, v246, 62
	v_readlane_b32 s10, v246, 63
	v_readlane_b32 s11, v245, 0
	v_readlane_b32 s12, v245, 1
	v_readlane_b32 s13, v245, 2
	v_readlane_b32 s14, v245, 3
	v_readlane_b32 s15, v245, 4
	v_lshlrev_b64 v[36:37], 1, v[38:39]
	v_cvt_pk_bf16_f32 v34, v28, v29
	v_cvt_pk_bf16_f32 v35, v30, v31
	v_lshl_add_u64 v[38:39], s[20:21], 0, v[36:37]
	global_store_dwordx2 v[38:39], v[34:35], off
	v_mul_f32_e32 v34, v29, v29
	v_fmac_f32_e32 v34, v28, v28
	v_fmac_f32_e32 v34, v30, v30
	v_fmac_f32_e32 v34, v31, v31
	s_nop 0
	v_cvt_pk_bf16_f32 v28, v24, v25
	v_mul_f32_e32 v25, v25, v25
	v_or_b32_e32 v30, 32, v36
	v_mov_b32_e32 v31, v37
	v_fmac_f32_e32 v25, v24, v24
	v_cvt_pk_bf16_f32 v29, v26, v27
	v_lshl_add_u64 v[30:31], s[20:21], 0, v[30:31]
	v_fmac_f32_e32 v25, v26, v26
	global_store_dwordx2 v[30:31], v[28:29], off
	v_fmac_f32_e32 v25, v27, v27
	v_add_f32_e32 v28, v34, v25
	s_nop 0
	v_cvt_pk_bf16_f32 v24, v20, v21
	v_mul_f32_e32 v21, v21, v21
	v_or_b32_e32 v26, 0x100, v36
	v_mov_b32_e32 v27, v37
	v_fmac_f32_e32 v21, v20, v20
	v_cvt_pk_bf16_f32 v25, v22, v23
	v_lshl_add_u64 v[26:27], s[20:21], 0, v[26:27]
	v_fmac_f32_e32 v21, v22, v22
	global_store_dwordx2 v[26:27], v[24:25], off
	v_fmac_f32_e32 v21, v23, v23
	v_add_f32_e32 v24, v28, v21
	v_or_b32_e32 v36, 0x120, v36
	s_nop 0
	v_cvt_pk_bf16_f32 v20, v16, v17
	v_mul_f32_e32 v17, v17, v17
	v_fmac_f32_e32 v17, v16, v16
	v_fmac_f32_e32 v17, v18, v18
	v_fmac_f32_e32 v17, v19, v19
	v_add_f32_e32 v16, v24, v17
	ds_bpermute_b32 v17, v150, v16
	v_cvt_pk_bf16_f32 v21, v18, v19
	v_lshl_add_u64 v[22:23], s[20:21], 0, v[36:37]
	global_store_dwordx2 v[22:23], v[20:21], off
	s_waitcnt lgkmcnt(0)
	v_add_f32_e32 v16, v16, v17
	ds_bpermute_b32 v17, v149, v16
	s_and_saveexec_b64 s[2:3], s[42:43]
	s_cbranch_execz .LBB0_685
	v_lshl_add_u64 v[18:19], v[32:33], 2, s[86:87]
	s_waitcnt lgkmcnt(0)
	v_add_f32_e32 v16, v16, v17
	global_atomic_add_f32 v[18:19], v16, off
.LBB0_685:
	s_or_b64 exec, exec, s[2:3]
	v_add_u32_e32 v16, 0xb0, v144
	s_waitcnt lgkmcnt(0)
	v_ashrrev_i32_e32 v17, 31, v16
	v_lshlrev_b64 v[18:19], 10, v[16:17]
	v_readlane_b32 s0, v246, 53
	v_lshl_add_u64 v[22:23], v[18:19], 0, v[142:143]
	v_readlane_b32 s1, v246, 54
	v_readlane_b32 s2, v246, 55
	v_readlane_b32 s3, v246, 56
	v_lshl_add_u64 v[24:25], v[22:23], 2, s[0:1]
	v_readlane_b32 s4, v246, 57
	v_readlane_b32 s5, v246, 58
	v_readlane_b32 s6, v246, 59
	v_readlane_b32 s7, v246, 60
	v_readlane_b32 s8, v246, 61
	v_readlane_b32 s9, v246, 62
	v_readlane_b32 s10, v246, 63
	v_readlane_b32 s11, v245, 0
	v_readlane_b32 s12, v245, 1
	v_readlane_b32 s13, v245, 2
	v_readlane_b32 s14, v245, 3
	v_readlane_b32 s15, v245, 4
	v_lshlrev_b64 v[20:21], 1, v[22:23]
	v_cvt_pk_bf16_f32 v18, v12, v13
	v_cvt_pk_bf16_f32 v19, v14, v15
	v_lshl_add_u64 v[22:23], s[20:21], 0, v[20:21]
	global_store_dwordx2 v[22:23], v[18:19], off
	v_mul_f32_e32 v18, v13, v13
	v_fmac_f32_e32 v18, v12, v12
	v_fmac_f32_e32 v18, v14, v14
	v_fmac_f32_e32 v18, v15, v15
	s_nop 0
	v_cvt_pk_bf16_f32 v12, v8, v9
	v_mul_f32_e32 v9, v9, v9
	v_or_b32_e32 v14, 32, v20
	v_mov_b32_e32 v15, v21
	v_fmac_f32_e32 v9, v8, v8
	v_cvt_pk_bf16_f32 v13, v10, v11
	v_lshl_add_u64 v[14:15], s[20:21], 0, v[14:15]
	v_fmac_f32_e32 v9, v10, v10
	global_store_dwordx2 v[14:15], v[12:13], off
	v_fmac_f32_e32 v9, v11, v11
	v_add_f32_e32 v12, v18, v9
	s_nop 0
	v_cvt_pk_bf16_f32 v8, v4, v5
	v_mul_f32_e32 v5, v5, v5
	v_or_b32_e32 v10, 0x100, v20
	v_mov_b32_e32 v11, v21
	v_fmac_f32_e32 v5, v4, v4
	v_cvt_pk_bf16_f32 v9, v6, v7
	v_lshl_add_u64 v[10:11], s[20:21], 0, v[10:11]
	v_fmac_f32_e32 v5, v6, v6
	global_store_dwordx2 v[10:11], v[8:9], off
	v_fmac_f32_e32 v5, v7, v7
	v_add_f32_e32 v8, v12, v5
	v_or_b32_e32 v20, 0x120, v20
	s_nop 0
	v_cvt_pk_bf16_f32 v4, v0, v1
	v_mul_f32_e32 v1, v1, v1
	v_fmac_f32_e32 v1, v0, v0
	v_fmac_f32_e32 v1, v2, v2
	v_fmac_f32_e32 v1, v3, v3
	v_add_f32_e32 v0, v8, v1
	ds_bpermute_b32 v1, v150, v0
	v_cvt_pk_bf16_f32 v5, v2, v3
	v_lshl_add_u64 v[6:7], s[20:21], 0, v[20:21]
	global_store_dwordx2 v[6:7], v[4:5], off
	s_waitcnt lgkmcnt(0)
	v_add_f32_e32 v0, v0, v1
	ds_bpermute_b32 v1, v149, v0
	s_and_saveexec_b64 s[2:3], s[42:43]
	s_cbranch_execz .LBB0_666
	v_lshl_add_u64 v[2:3], v[16:17], 2, s[86:87]
	s_waitcnt lgkmcnt(0)
	v_add_f32_e32 v0, v0, v1
	global_atomic_add_f32 v[2:3], v0, off
	s_branch .LBB0_666
